# phase 4 sample merged GEMMs as 24 independent store-only jobs (no flag chain), f32 partials summed + bf16 in phase 5 start (same association); hg_pass3 restructure kept
# speedup vs baseline: 1.0930x; 1.0118x over previous
.LBB0_829:
	s_lshr_b32 s98, s94, 2
	s_and_b32 s98, s98, 1
	s_add_i32 s98, s98, 64
	s_and_b32 s99, s94, 3
	v_writelane_b32 v214, s98, 0
	v_writelane_b32 v214, s99, 1
	s_movk_i32 s98, 0x0
	v_writelane_b32 v214, s98, 2
	s_movk_i32 s98, 0x0
	v_writelane_b32 v214, s98, 3
	s_branch .Lepi_merge

.LBB0_845:
	s_lshr_b32 s98, s94, 2
	s_and_b32 s98, s98, 1
	s_add_i32 s98, s98, 64
	s_and_b32 s99, s94, 3
	v_writelane_b32 v214, s98, 0
	v_writelane_b32 v214, s99, 1
	s_movk_i32 s98, 0x10
	v_writelane_b32 v214, s98, 2
	s_movk_i32 s98, 0x5
	v_writelane_b32 v214, s98, 3
	s_branch .Lepi_merge

.LBB0_861:
	s_lshr_b32 s98, s94, 2
	s_and_b32 s98, s98, 1
	s_add_i32 s98, s98, 64
	s_and_b32 s99, s94, 3
	v_writelane_b32 v214, s98, 0
	v_writelane_b32 v214, s99, 1
	s_movk_i32 s98, 0x20
	v_writelane_b32 v214, s98, 2
	s_movk_i32 s98, 0xa
	v_writelane_b32 v214, s98, 3
	s_branch .Lepi_merge

.Lepi_merge:
	s_load_dwordx2 s[98:99], s[0:1], 0xd8
	s_load_dwordx2 s[100:101], s[0:1], 0xe0
	v_lshrrev_b32_e32 v196, 8, v156
	v_and_b32_e32 v197, 15, v156
	v_lshl_or_b32 v196, v196, 6, v197
	v_bfe_u32 v197, v156, 6, 2
	v_bfe_u32 v198, v156, 4, 2
	v_lshlrev_b32_e32 v198, 2, v198
	v_lshl_or_b32 v197, v197, 5, v198
	v_readlane_b32 vcc_lo, v214, 0
	v_readlane_b32 vcc_hi, v214, 1
	s_nop 1
	s_lshl_b32 vcc_lo, vcc_lo, 8
	s_lshl_b32 vcc_hi, vcc_hi, 8
	v_add_u32_e32 v196, vcc_lo, v196
	v_add_u32_e32 v197, vcc_hi, v197
	v_readlane_b32 vcc_hi, v214, 3
	s_and_b32 vcc_hi, vcc_hi, 3
	s_waitcnt lgkmcnt(0)
	s_add_u32 s100, s100, 0x2032400
	s_addc_u32 s101, s101, 0
	s_lshl_b32 vcc_lo, vcc_hi, 11
	s_add_u32 s100, s100, vcc_lo
	s_addc_u32 s101, s101, 0
	v_mov_b32_e32 v198, 0x3c00
	v_mul_hi_u32 v201, v196, v198
	v_mul_lo_u32 v200, v196, v198
	v_lshlrev_b32_e32 v199, 1, v197
	v_mov_b32_e32 v198, 0
	v_add_co_u32_e32 v200, vcc, v200, v199
	v_addc_co_u32_e32 v201, vcc, 0, v201, vcc
	v_lshl_add_u64 v[200:201], v[200:201], 0, s[100:101]
	v_lshlrev_b32_e32 v199, 2, v197
	v_lshrrev_b32_e32 v203, 20, v196
	v_lshlrev_b32_e32 v202, 12, v196
	v_add_co_u32_e32 v202, vcc, v202, v199
	v_addc_co_u32_e32 v203, vcc, 0, v203, vcc
	v_readlane_b32 vcc_hi, v214, 3
	s_lshr_b32 vcc_hi, vcc_hi, 2
	s_cmp_eq_u32 vcc_hi, 0
	s_cbranch_scc1 .Lepi_dest0
	s_lshl_b32 vcc_hi, vcc_hi, 21
	s_add_u32 s98, s40, vcc_hi
	s_addc_u32 s99, s41, 0
	s_sub_u32 s98, s98, 0x29d0000
	s_subb_u32 s99, s99, 0
.Lepi_dest0:
	v_lshl_add_u64 v[202:203], v[202:203], 0, s[98:99]
	v_mov_b32_e32 v204, v202
	v_mov_b32_e32 v205, v203
	v_readlane_b32 vcc_hi, v214, 2
	s_and_b32 vcc_hi, vcc_hi, 15
	s_cmp_eq_u32 vcc_hi, 2
	s_cbranch_scc0 .Lepi_p1
	s_load_dwordx2 s[98:99], s[0:1], 0xe0
	v_readlane_b32 vcc_lo, v214, 0
	s_waitcnt lgkmcnt(0)
	s_add_u32 s100, s98, 0x13034000
	s_addc_u32 s101, s99, 0
	s_add_u32 s98, s98, 0x117b0000
	s_addc_u32 s99, s99, 0
	s_cmp_ge_u32 vcc_lo, 64
	s_cselect_b32 s98, s100, s98
	s_cselect_b32 s99, s101, s99
	v_lshlrev_b32_e32 v199, 1, v197
	v_lshrrev_b32_e32 v205, 21, v196
	v_lshlrev_b32_e32 v204, 11, v196
	v_add_co_u32_e32 v204, vcc, v204, v199
	v_addc_co_u32_e32 v205, vcc, 0, v205, vcc
	v_lshl_add_u64 v[204:205], v[204:205], 0, s[98:99]

.LBB0_921:
	s_load_dwordx2 s[98:99], s[0:1], 0xd8
	v_lshrrev_b32_e32 v0, 8, v156
	v_lshl_add_u32 v0, s94, 1, v0
	v_and_b32_e32 v1, 0xff, v156
	v_lshlrev_b32_e32 v2, 12, v0
	v_lshl_add_u32 v2, v1, 4, v2
	v_lshlrev_b32_e32 v3, 11, v0
	v_lshl_add_u32 v3, v1, 3, v3
	v_cmp_gt_u32_e32 vcc, 0x200, v0
	s_and_saveexec_b64 s[100:101], vcc
	s_cbranch_execz .Lcomb_done
	s_waitcnt lgkmcnt(0)
	s_add_u32 s98, s98, 0x4000000
	s_addc_u32 s99, s99, 0
	global_load_dwordx4 v[4:7], v2, s[98:99]
	s_add_u32 s98, s40, 0x1830000
	s_addc_u32 s99, s41, 0
	global_load_dwordx4 v[8:11], v2, s[98:99]
	s_add_u32 s98, s40, 0x1a30000
	s_addc_u32 s99, s41, 0
	global_load_dwordx4 v[12:15], v2, s[98:99]
	s_add_u32 s98, s40, 0x15034000
	s_addc_u32 s99, s41, 0
	s_waitcnt vmcnt(1)
	v_pk_add_f32 v[4:5], v[8:9], v[4:5]
	v_pk_add_f32 v[6:7], v[10:11], v[6:7]
	s_waitcnt vmcnt(0)
	v_pk_add_f32 v[4:5], v[12:13], v[4:5]
	v_pk_add_f32 v[6:7], v[14:15], v[6:7]
	s_nop 0
	v_cvt_pk_bf16_f32 v4, v4, v5
	v_cvt_pk_bf16_f32 v5, v6, v7
	global_store_dwordx2 v3, v[4:5], s[98:99]
.Lcomb_done:
	s_or_b64 exec, exec, s[100:101]
	s_mov_b32 s2, s94
	s_mov_b64 s[4:5], s[0:1]
	s_load_dwordx4 s[12:15], s[4:5], 0xd8
	v_mov_b32_e32 v8, v156
	s_waitcnt lgkmcnt(0)
	s_add_u32 s18, s14, 0x2030000
	s_addc_u32 s19, s15, 0
	s_cmpk_lt_i32 s2, 0x100
	s_cselect_b64 s[8:9], -1, 0
	s_cmpk_gt_i32 s2, 0xff
	v_readfirstlane_b32 s6, v8
	s_cbranch_scc1 .LBB0_947
	s_ashr_i32 s3, s2, 31
	s_lshr_b32 s4, s3, 29
	s_add_i32 s7, s2, s4
	s_and_b32 s4, s7, -8
	s_sub_i32 s10, s2, s4
	s_cmp_gt_i32 s10, -1
	s_cbranch_scc0 .LBB0_924
	s_lshl_b32 s20, s10, 5
	s_cbranch_execz .LBB0_925
	s_branch .LBB0_926

.LBB0_943:
	v_writelane_b32 v214, s59, 0
	v_writelane_b32 v214, s60, 1
	s_movk_i32 s98, 0x30
	v_writelane_b32 v214, s98, 2
	s_movk_i32 s98, 0x0
	v_writelane_b32 v214, s98, 3
	s_branch .Lepi_merge

.LBB0_969:
	v_writelane_b32 v214, s61, 0
	v_writelane_b32 v214, s62, 1
	s_movk_i32 s98, 0x41
	v_writelane_b32 v214, s98, 2
	s_movk_i32 s98, 0x1
	v_writelane_b32 v214, s98, 3
	s_branch .Lepi_merge

.LBB0_995:
	v_writelane_b32 v214, s63, 0
	v_writelane_b32 v214, s64, 1
	s_movk_i32 s98, 0x52
	v_writelane_b32 v214, s98, 2
	s_movk_i32 s98, 0x2
	v_writelane_b32 v214, s98, 3
	s_branch .Lepi_merge
